# DIFF: ALiBi(sub1) under PV(sub0) MFMA 0-7 and exp(sub1) under MFMA 8-15, separate exp(sub1) block removed
# speedup vs baseline: 1.0199x; 1.0112x over previous
; #define MFMA(a, b, c) __builtin_amdgcn_mfma_f32_32x32x16_bf16((a), (b), (c), 0, 0, 0)
; DI u32 pk2(float a, float b) { f2_t v = {a, b}; bf2_t r = __builtin_convertvector(v, bf2_t); return __builtin_bit_cast(u32, r); }
; #define DIFF_MASK(sv, sub_) do { if (needmask) { _Pragma("unroll") for (int r = 0; r < 16; ++r) { const int kl_ = (sub_) * 32 + ((r < 8) ? (8 * g2 + r) : (16 + 8 * g2 + (r - 8))); \
;           if ((pki[kl_] >> 6) > (((int)qposf) >> 6)) sv[r] = -__builtin_inff(); } } } while (0)
; template <bool DIFF>
; DI void attn_phase(const AttnArgs& a, char* lds) {
;     ...
;           DIFF_ALIBI(s0, 0);
;           DIFF_MASK(s0, 0);
;           float ps = 0.f;
; #pragma unroll
;           for (int r = 0; r < 16; ++r) { s0[r] = __builtin_amdgcn_exp2f(s0[r]); ps += s0[r]; }
;           l_sum += ps;
;           asm volatile("" : "+v"(l_sum));
; #pragma unroll
;           for (int i = 0; i < NDS; ++i) { __builtin_amdgcn_sched_group_barrier(0x008, 1, 0); __builtin_amdgcn_sched_group_barrier(0x002, 9, 0); }
;         }
;         __builtin_amdgcn_sched_barrier(0);
;         {
;           bf16x8 vf[NM];
; #pragma unroll
;           for (int s2 = 0; s2 < 2; ++s2) {
; #pragma unroll
;             for (int m = 0; m < NM; ++m) vf[m] = *(const bf16x8*)(sb + voffb + m * 4096 + (((2 * s2) ^ vx) << 4));
;             u32x4 pw;
;             pw[0] = pk2(s0[8 * s2], s0[8 * s2 + 1]); pw[1] = pk2(s0[8 * s2 + 2], s0[8 * s2 + 3]);
;             pw[2] = pk2(s0[8 * s2 + 4], s0[8 * s2 + 5]); pw[3] = pk2(s0[8 * s2 + 6], s0[8 * s2 + 7]);
;             const bf16x8 pf = __builtin_bit_cast(bf16x8, pw);
; #pragma unroll
;             for (int m = 0; m < NM; ++m) o[m] = MFMA(vf[m], pf, o[m]);
;           }
;           DIFF_ALIBI(s1, 1);
;           DIFF_MASK(s1, 1);
.LBB0_605:
	v_exp_f32_e32 v11, v11
	v_exp_f32_e32 v9, v9
	v_exp_f32_e32 v10, v10
	v_exp_f32_e32 v8, v8
	v_bitop3_b32 v0, v0, v3, 7 bitop3:0x78
	v_add_f32_e32 v3, 0, v11
	v_exp_f32_e32 v165, v7
	v_add_f32_e32 v3, v9, v3
	v_exp_f32_e32 v166, v6
	v_add_f32_e32 v3, v10, v3
	v_exp_f32_e32 v167, v5
	v_add_f32_e32 v3, v8, v3
	v_exp_f32_e32 v168, v4
	v_add_f32_e32 v3, v165, v3
	v_exp_f32_e32 v164, v164
	v_lshlrev_b32_e32 v2, 7, v2
	v_add_f32_e32 v3, v166, v3
	v_exp_f32_e32 v169, v162
	v_and_b32_e32 v2, 0xf80, v2
	v_add_f32_e32 v3, v167, v3
	v_exp_f32_e32 v170, v160
	v_add_f32_e32 v3, v168, v3
	v_exp_f32_e32 v171, v161
	v_add_f32_e32 v3, v164, v3
	v_exp_f32_e32 v15, v15
	v_add_f32_e32 v3, v169, v3
	v_exp_f32_e32 v14, v14
	v_add_f32_e32 v3, v170, v3
	v_exp_f32_e32 v172, v13
	v_add_f32_e32 v3, v171, v3
	v_exp_f32_e32 v173, v12
	v_add_f32_e32 v3, v15, v3
	v_add_f32_e32 v3, v14, v3
	v_add_f32_e32 v3, v172, v3
	v_add_f32_e32 v3, v173, v3
	v_add_f32_e32 v162, v226, v3
	v_add_u32_e32 v160, s84, v2
	v_lshlrev_b32_e32 v161, 4, v0
	v_add_u32_e32 v0, v160, v161
	v_cvt_pk_bf16_f32 v6, v11, v9
	v_cvt_pk_bf16_f32 v7, v10, v8
	v_cvt_pk_bf16_f32 v8, v165, v166
	v_cvt_pk_bf16_f32 v9, v167, v168
	v_cvt_pk_bf16_f32 v10, v164, v169
	v_cvt_pk_bf16_f32 v11, v170, v171
	v_cvt_pk_bf16_f32 v12, v15, v14
	v_cvt_pk_bf16_f32 v13, v172, v173
	v_add_u32_e32 v14, 0x10180, v227
	v_xad_u32 v15, v161, 32, v160
	ds_read_b128 v[164:167], v14
	ds_read_b128 v[168:171], v14 offset:16
	ds_read_b128 v[172:175], v14 offset:64
	ds_read_b128 v[248:251], v14 offset:80
	ds_read_b128 v[2:5], v0 offset:32768
	ds_read_b128 v[228:231], v0 offset:36864
	ds_read_b128 v[232:235], v0 offset:40960
	ds_read_b128 v[236:239], v0 offset:45056
	ds_read_b128 v[240:243], v0 offset:49152
	ds_read_b128 v[244:247], v0 offset:53248
	s_and_b64 vcc, exec, s[8:9]
	s_waitcnt lgkmcnt(5)
	v_mfma_f32_32x32x16_bf16 v[128:143], v[2:5], v[6:9], v[128:143]
	ds_read_b128 v[2:5], v0 offset:57344
	v_sub_f32_e32 v164, v221, v164
	v_sub_f32_e32 v165, v221, v165
	v_fma_f32 v164, -v223, |v164|, v144
	v_fma_f32 v165, -v223, |v165|, v145
	s_waitcnt lgkmcnt(5)
	v_mfma_f32_32x32x16_bf16 v[112:127], v[228:231], v[6:9], v[112:127]
	ds_read_b128 v[228:231], v0 offset:61440
	v_sub_f32_e32 v166, v221, v166
	v_sub_f32_e32 v167, v221, v167
	v_fma_f32 v166, -v223, |v166|, v146
	v_fma_f32 v167, -v223, |v167|, v147
	s_waitcnt lgkmcnt(5)
	v_mfma_f32_32x32x16_bf16 v[96:111], v[232:235], v[6:9], v[96:111]
	ds_read_b128 v[232:235], v15 offset:32768
	v_sub_f32_e32 v168, v221, v168
	v_sub_f32_e32 v169, v221, v169
	v_fma_f32 v168, -v223, |v168|, v148
	v_fma_f32 v169, -v223, |v169|, v149
	s_waitcnt lgkmcnt(5)
	v_mfma_f32_32x32x16_bf16 v[80:95], v[236:239], v[6:9], v[80:95]
	ds_read_b128 v[236:239], v15 offset:36864
	v_sub_f32_e32 v170, v221, v170
	v_sub_f32_e32 v171, v221, v171
	v_fma_f32 v170, -v223, |v170|, v150
	v_fma_f32 v171, -v223, |v171|, v151
	s_waitcnt lgkmcnt(5)
	v_mfma_f32_32x32x16_bf16 v[64:79], v[240:243], v[6:9], v[64:79]
	ds_read_b128 v[240:243], v15 offset:40960
	v_sub_f32_e32 v172, v221, v172
	v_sub_f32_e32 v173, v221, v173
	v_fma_f32 v172, -v223, |v172|, v152
	v_fma_f32 v173, -v223, |v173|, v153
	s_waitcnt lgkmcnt(5)
	v_mfma_f32_32x32x16_bf16 v[48:63], v[244:247], v[6:9], v[48:63]
	ds_read_b128 v[244:247], v15 offset:45056
	v_sub_f32_e32 v174, v221, v174
	v_sub_f32_e32 v175, v221, v175
	v_fma_f32 v174, -v223, |v174|, v154
	v_fma_f32 v175, -v223, |v175|, v155
	s_waitcnt lgkmcnt(5)
	v_mfma_f32_32x32x16_bf16 v[32:47], v[2:5], v[6:9], v[32:47]
	ds_read_b128 v[2:5], v15 offset:49152
	v_sub_f32_e32 v248, v221, v248
	v_sub_f32_e32 v249, v221, v249
	v_fma_f32 v248, -v223, |v248|, v156
	v_fma_f32 v249, -v223, |v249|, v157
	s_waitcnt lgkmcnt(5)
	v_mfma_f32_32x32x16_bf16 v[16:31], v[228:231], v[6:9], v[16:31]
	ds_read_b128 v[228:231], v15 offset:53248
	v_sub_f32_e32 v250, v221, v250
	v_sub_f32_e32 v251, v221, v251
	v_fma_f32 v250, -v223, |v250|, v158
	v_fma_f32 v251, -v223, |v251|, v159
	s_cbranch_vccnz .Ldiff_nomask1
	ds_read_b128 v[146:149], v163 offset:128
	s_waitcnt lgkmcnt(0)
	v_ashrrev_i32_e32 v144, 6, v146
	v_cmp_le_i32_e32 vcc, v144, v224
	v_ashrrev_i32_e32 v144, 6, v147
	s_nop 0
	v_cndmask_b32_e32 v164, v216, v164, vcc
	v_cmp_le_i32_e32 vcc, v144, v224
	v_ashrrev_i32_e32 v144, 6, v148
	s_nop 0
	v_cndmask_b32_e32 v165, v216, v165, vcc
	v_cmp_le_i32_e32 vcc, v144, v224
	v_ashrrev_i32_e32 v144, 6, v149
	s_nop 0
	v_cndmask_b32_e32 v166, v216, v166, vcc
	v_cmp_le_i32_e32 vcc, v144, v224
	v_add_u32_e32 v144, 0x10090, v227
	ds_read_b128 v[146:149], v144
	v_cndmask_b32_e32 v167, v216, v167, vcc
	s_waitcnt lgkmcnt(0)
	v_ashrrev_i32_e32 v144, 6, v146
	v_cmp_le_i32_e32 vcc, v144, v224
	v_ashrrev_i32_e32 v144, 6, v147
	s_nop 0
	v_cndmask_b32_e32 v168, v216, v168, vcc
	v_cmp_le_i32_e32 vcc, v144, v224
	v_ashrrev_i32_e32 v144, 6, v148
	s_nop 0
	v_cndmask_b32_e32 v169, v216, v169, vcc
	v_cmp_le_i32_e32 vcc, v144, v224
	v_ashrrev_i32_e32 v144, 6, v149
	s_nop 0
	v_cndmask_b32_e32 v170, v216, v170, vcc
	v_cmp_le_i32_e32 vcc, v144, v224
	v_add_u32_e32 v144, 0x100c0, v227
	ds_read_b128 v[146:149], v144
	v_cndmask_b32_e32 v171, v216, v171, vcc
	s_waitcnt lgkmcnt(0)
	v_ashrrev_i32_e32 v144, 6, v146
	v_cmp_le_i32_e32 vcc, v144, v224
	v_ashrrev_i32_e32 v144, 6, v147
	s_nop 0
	v_cndmask_b32_e32 v172, v216, v172, vcc
	v_cmp_le_i32_e32 vcc, v144, v224
	v_ashrrev_i32_e32 v144, 6, v148
	s_nop 0
	v_cndmask_b32_e32 v173, v216, v173, vcc
	v_cmp_le_i32_e32 vcc, v144, v224
	v_ashrrev_i32_e32 v144, 6, v149
	s_nop 0
	v_cndmask_b32_e32 v174, v216, v174, vcc
	v_cmp_le_i32_e32 vcc, v144, v224
	v_add_u32_e32 v144, 0x100d0, v227
	ds_read_b128 v[146:149], v144
	v_cndmask_b32_e32 v175, v216, v175, vcc
	s_waitcnt lgkmcnt(0)
	v_ashrrev_i32_e32 v144, 6, v146
	v_cmp_le_i32_e32 vcc, v144, v224
	v_ashrrev_i32_e32 v144, 6, v147
	s_nop 0
	v_cndmask_b32_e32 v248, v216, v248, vcc
	v_cmp_le_i32_e32 vcc, v144, v224
	v_ashrrev_i32_e32 v144, 6, v148
	s_nop 0
	v_cndmask_b32_e32 v249, v216, v249, vcc
	v_cmp_le_i32_e32 vcc, v144, v224
	v_ashrrev_i32_e32 v144, 6, v149
	s_nop 0
	v_cndmask_b32_e32 v250, v216, v250, vcc
	v_cmp_le_i32_e32 vcc, v144, v224
	s_nop 1
	v_cndmask_b32_e32 v251, v216, v251, vcc
; #define MFMA(a, b, c) __builtin_amdgcn_mfma_f32_32x32x16_bf16((a), (b), (c), 0, 0, 0)
; DI u32 pk2(float a, float b) { f2_t v = {a, b}; bf2_t r = __builtin_convertvector(v, bf2_t); return __builtin_bit_cast(u32, r); }
; #define DIFF_MASK(sv, sub_) do { if (needmask) { _Pragma("unroll") for (int r = 0; r < 16; ++r) { const int kl_ = (sub_) * 32 + ((r < 8) ? (8 * g2 + r) : (16 + 8 * g2 + (r - 8))); \
;           if ((pki[kl_] >> 6) > (((int)qposf) >> 6)) sv[r] = -__builtin_inff(); } } } while (0)
; template <bool DIFF>
; DI void attn_phase(const AttnArgs& a, char* lds) {
;     ...
;           DIFF_ALIBI(s1, 1);
;           DIFF_MASK(s1, 1);
;           float ps = 0.f;
; #pragma unroll
;           for (int r = 0; r < 16; ++r) { s1[r] = __builtin_amdgcn_exp2f(s1[r]); ps += s1[r]; }
;           l_sum += ps;
;           asm volatile("" : "+v"(l_sum));
; #pragma unroll
;           for (int i = 0; i < 2 * NM; ++i) { __builtin_amdgcn_sched_group_barrier(0x008, 1, 0); __builtin_amdgcn_sched_group_barrier(0x002, 4, 0); }
;         }
;         __builtin_amdgcn_sched_barrier(0);
;         {
; #pragma unroll
;           for (int s2 = 0; s2 < 2; ++s2) {
;             bf16x8 vf[NM];
; #pragma unroll
;             for (int m = 0; m < NM; ++m) vf[m] = *(const bf16x8*)(sb + voffb + m * 4096 + (((4 + 2 * s2) ^ vx) << 4));
;             u32x4 pw;
;             pw[0] = pk2(s1[8 * s2], s1[8 * s2 + 1]); pw[1] = pk2(s1[8 * s2 + 2], s1[8 * s2 + 3]);
;             pw[2] = pk2(s1[8 * s2 + 4], s1[8 * s2 + 5]); pw[3] = pk2(s1[8 * s2 + 6], s1[8 * s2 + 7]);
;             const bf16x8 pf = __builtin_bit_cast(bf16x8, pw);
; #pragma unroll
;             for (int m = 0; m < NM; ++m) o[m] = MFMA(vf[m], pf, o[m]);
;           }
;         }
.Ldiff_nomask1:
	s_waitcnt lgkmcnt(5)
	v_mfma_f32_32x32x16_bf16 v[128:143], v[232:235], v[10:13], v[128:143]
	ds_read_b128 v[232:235], v15 offset:57344
	v_exp_f32_e32 v0, v164
	v_exp_f32_e32 v9, v165
	v_add_f32_e32 v253, 0, v0
	v_add_f32_e32 v253, v9, v253
	s_waitcnt lgkmcnt(5)
	v_mfma_f32_32x32x16_bf16 v[112:127], v[236:239], v[10:13], v[112:127]
	ds_read_b128 v[236:239], v15 offset:61440
	v_exp_f32_e32 v144, v166
	v_exp_f32_e32 v146, v167
	v_add_f32_e32 v253, v144, v253
	v_add_f32_e32 v253, v146, v253
	s_waitcnt lgkmcnt(5)
	v_mfma_f32_32x32x16_bf16 v[96:111], v[240:243], v[10:13], v[96:111]
	v_exp_f32_e32 v147, v168
	v_exp_f32_e32 v148, v169
	v_add_f32_e32 v253, v147, v253
	v_add_f32_e32 v253, v148, v253
	s_waitcnt lgkmcnt(4)
	v_mfma_f32_32x32x16_bf16 v[80:95], v[244:247], v[10:13], v[80:95]
	v_exp_f32_e32 v149, v170
	v_exp_f32_e32 v150, v171
	v_add_f32_e32 v253, v149, v253
	v_add_f32_e32 v253, v150, v253
	s_waitcnt lgkmcnt(3)
	v_mfma_f32_32x32x16_bf16 v[64:79], v[2:5], v[10:13], v[64:79]
	v_exp_f32_e32 v151, v172
	v_exp_f32_e32 v145, v173
	v_add_f32_e32 v253, v151, v253
	v_add_f32_e32 v253, v145, v253
	s_waitcnt lgkmcnt(2)
	v_mfma_f32_32x32x16_bf16 v[48:63], v[228:231], v[10:13], v[48:63]
	v_exp_f32_e32 v152, v174
	v_exp_f32_e32 v153, v175
	v_add_f32_e32 v253, v152, v253
	v_add_f32_e32 v253, v153, v253
	s_waitcnt lgkmcnt(1)
	v_mfma_f32_32x32x16_bf16 v[32:47], v[232:235], v[10:13], v[32:47]
	v_exp_f32_e32 v154, v248
	v_exp_f32_e32 v155, v249
	v_add_f32_e32 v253, v154, v253
	v_add_f32_e32 v253, v155, v253
	s_waitcnt lgkmcnt(0)
	v_mfma_f32_32x32x16_bf16 v[16:31], v[236:239], v[10:13], v[16:31]
	v_exp_f32_e32 v14, v250
	v_exp_f32_e32 v15, v251
	v_add_f32_e32 v253, v14, v253
	v_add_f32_e32 v253, v15, v253
	v_add_f32_e32 v226, v162, v253
	v_xad_u32 v156, v161, 64, v160
	ds_read_b128 v[2:5], v156 offset:32768
	ds_read_b128 v[228:231], v156 offset:36864
	ds_read_b128 v[232:235], v156 offset:40960
	ds_read_b128 v[236:239], v156 offset:45056
	ds_read_b128 v[240:243], v156 offset:49152
	ds_read_b128 v[244:247], v156 offset:53248
	ds_read_b128 v[248:251], v156 offset:57344
	v_cvt_pk_bf16_f32 v6, v0, v9
	v_cvt_pk_bf16_f32 v7, v144, v146
	v_cvt_pk_bf16_f32 v8, v147, v148
	v_cvt_pk_bf16_f32 v9, v149, v150
	v_xad_u32 v0, v161, s74, v160
	v_cvt_pk_bf16_f32 v10, v151, v145
	v_cvt_pk_bf16_f32 v11, v152, v153
	v_cvt_pk_bf16_f32 v12, v154, v155
	v_cvt_pk_bf16_f32 v13, v14, v15
	s_waitcnt lgkmcnt(6)
	v_mfma_f32_32x32x16_bf16 v[128:143], v[2:5], v[6:9], v[128:143]
	ds_read_b128 v[2:5], v156 offset:61440
	s_waitcnt lgkmcnt(6)
	v_mfma_f32_32x32x16_bf16 v[112:127], v[228:231], v[6:9], v[112:127]
	ds_read_b128 v[228:231], v0 offset:32768
	s_waitcnt lgkmcnt(6)
	v_mfma_f32_32x32x16_bf16 v[96:111], v[232:235], v[6:9], v[96:111]
	ds_read_b128 v[232:235], v0 offset:36864
	s_waitcnt lgkmcnt(6)
	v_mfma_f32_32x32x16_bf16 v[80:95], v[236:239], v[6:9], v[80:95]
	ds_read_b128 v[236:239], v0 offset:40960
	s_waitcnt lgkmcnt(6)
	v_mfma_f32_32x32x16_bf16 v[64:79], v[240:243], v[6:9], v[64:79]
	ds_read_b128 v[240:243], v0 offset:45056
	s_waitcnt lgkmcnt(6)
	v_mfma_f32_32x32x16_bf16 v[48:63], v[244:247], v[6:9], v[48:63]
	ds_read_b128 v[244:247], v0 offset:49152
	s_waitcnt lgkmcnt(6)
	v_mfma_f32_32x32x16_bf16 v[32:47], v[248:251], v[6:9], v[32:47]
	ds_read_b128 v[248:251], v0 offset:53248
	s_waitcnt lgkmcnt(6)
	v_mfma_f32_32x32x16_bf16 v[16:31], v[2:5], v[6:9], v[16:31]
	ds_read_b128 v[2:5], v0 offset:57344
	s_waitcnt lgkmcnt(6)
	v_mfma_f32_32x32x16_bf16 v[128:143], v[228:231], v[10:13], v[128:143]
	ds_read_b128 v[228:231], v0 offset:61440
	s_waitcnt lgkmcnt(6)
	v_mfma_f32_32x32x16_bf16 v[112:127], v[232:235], v[10:13], v[112:127]
	s_waitcnt lgkmcnt(5)
	v_mfma_f32_32x32x16_bf16 v[96:111], v[236:239], v[10:13], v[96:111]
	s_waitcnt lgkmcnt(4)
	v_mfma_f32_32x32x16_bf16 v[80:95], v[240:243], v[10:13], v[80:95]
	s_waitcnt lgkmcnt(3)
	v_mfma_f32_32x32x16_bf16 v[64:79], v[244:247], v[10:13], v[64:79]
	s_waitcnt lgkmcnt(2)
	v_mfma_f32_32x32x16_bf16 v[48:63], v[248:251], v[10:13], v[48:63]
	s_waitcnt lgkmcnt(1)
	v_mfma_f32_32x32x16_bf16 v[32:47], v[2:5], v[10:13], v[32:47]
	s_waitcnt lgkmcnt(0)
	v_mfma_f32_32x32x16_bf16 v[16:31], v[228:231], v[10:13], v[16:31]
